# K_nope up-projection epilogue: the two np=4 row-scale partial loads issued together (fast path) instead of two serialized load-wait loops
# baseline (speedup 1.0000x reference)
;     static __device__ __forceinline__ float rowsum(const float* ssq, int row, int np) {
;         const f32x4* p = (const f32x4*)(ssq + (size_t)row * np);
;         float s = 0.f;
;         for (int i = 0; i < np / 4; ++i) { const f32x4 v = p[i]; s += (v[0] + v[1]) + (v[2] + v[3]); }
;         return s;
;     }
;     __device__ __forceinline__ void row_scales(int rowbase, int lane, int fr, float (&rs)[2]) const {
;         rs[0] = rsqrtf(rowsum(ssq, rowbase + lane, np) * inv_dim + EPS); rs[1] = rsqrtf(rowsum(ssq, rowbase + 128 + lane, np) * inv_dim + EPS);
;     }
.LBB0_407:
	s_andn2_b64 vcc, exec, s[6:7]
	s_cbranch_vccnz .LBB0_415
	v_readlane_b32 s6, v255, 16
	v_readlane_b32 s7, v255, 17
	v_add_u32_e32 v3, s2, v194
	v_ashrrev_i32_e32 v134, 31, v3
	v_cndmask_b32_e64 v0, 0, 1, s[6:7]
	v_cmp_ne_u32_e64 s[40:41], 1, v0
	s_andn2_b64 vcc, exec, s[6:7]
	v_mov_b32_e32 v0, 0
	s_cbranch_vccnz .LBB0_411
	v_readlane_b32 s6, v255, 22
	v_readlane_b32 s7, v255, 23
	v_readlane_b32 s14, v255, 61
	v_readlane_b32 s15, v255, 62
	v_mov_b64_e32 v[132:133], s[6:7]
	v_mad_u64_u32 v[132:133], s[6:7], s14, v3, v[132:133]
	v_mul_lo_u32 v0, s14, v134
	v_mul_lo_u32 v134, s15, v3
	v_add3_u32 v133, v134, v133, v0
	v_mov_b32_e32 v0, 0
	v_readlane_b32 s1, v255, 42
	s_cmp_lg_u32 s1, 1
	s_cbranch_scc1 .LBB0_410
	global_load_dwordx4 v[160:163], v[132:133], off
	v_add_u32_e32 v3, 0x80, v3
	v_readlane_b32 s6, v255, 22
	v_ashrrev_i32_e32 v132, 31, v3
	v_readlane_b32 s14, v255, 61
	v_readlane_b32 s7, v255, 23
	v_readlane_b32 s15, v255, 62
	v_mul_lo_u32 v134, s14, v132
	v_mov_b64_e32 v[132:133], s[6:7]
	v_mul_lo_u32 v135, s15, v3
	v_mad_u64_u32 v[132:133], s[6:7], s14, v3, v[132:133]
	v_add3_u32 v133, v135, v133, v134
	global_load_dwordx4 v[176:179], v[132:133], off
	v_mov_b32_e32 v134, 0
	s_waitcnt vmcnt(1)
	v_add_f32_e32 v136, v160, v161
	v_add_f32_e32 v137, v162, v163
	v_add_f32_e32 v136, v136, v137
	v_add_f32_e32 v0, v0, v136
	s_waitcnt vmcnt(0)
	v_add_f32_e32 v136, v176, v177
	v_add_f32_e32 v137, v178, v179
	v_add_f32_e32 v3, v136, v137
	v_add_f32_e32 v134, v134, v3
	s_branch .LBB0_414
